# attention: next unit's Q rows (LDS-DMA) and first two K/V tiles requested right after the end-of-unit barrier, before the output ladder; prologue loads only for the first unit
# speedup vs baseline: 1.0165x; 1.0046x over previous
.LBB0_737:
	v_mov_b32_e32 v130, v210
	s_add_i32 s74, s74, 1
	v_ashrrev_i32_e32 v189, 31, v188
	v_lshl_add_u64 v[128:129], v[188:189], 0, s[46:47]
	v_lshlrev_b32_e32 v130, 2, v130
	v_lshlrev_b64 v[140:141], 11, v[128:129]
	v_lshl_or_b32 v140, s75, 1, v140
	v_ashrrev_i32_e32 v131, 31, v130
	v_lshl_add_u64 v[128:129], s[48:49], 0, v[140:141]
	v_lshlrev_b64 v[136:137], 1, v[130:131]
	v_lshl_add_u64 v[134:135], v[128:129], 0, v[136:137]
	v_lshlrev_b32_e32 v215, 3, v206
	global_load_dwordx2 v[204:205], v215, s[52:53]
	global_load_dwordx2 v[160:161], v[134:135], off
	global_load_dwordx2 v[162:163], v[134:135], off offset:16
	global_load_dwordx2 v[164:165], v[134:135], off offset:32
	global_load_dwordx2 v[166:167], v[134:135], off offset:48
	global_load_dwordx2 v[168:169], v[134:135], off offset:64
	global_load_dwordx2 v[170:171], v[134:135], off offset:80
	global_load_dwordx2 v[172:173], v[134:135], off offset:96
	global_load_dwordx2 v[174:175], v[134:135], off offset:112
	global_load_dwordx2 v[202:203], v[134:135], off offset:128
	global_load_dwordx2 v[244:245], v[134:135], off offset:160
	global_load_dwordx2 v[246:247], v[134:135], off offset:176
	global_load_dwordx2 v[248:249], v[134:135], off offset:192
	global_load_dwordx2 v[250:251], v[134:135], off offset:208
	global_load_dwordx2 v[252:253], v[134:135], off offset:224
	global_load_dwordx2 v[254:255], v[134:135], off offset:240
	s_lshr_b32 s0, s87, 2
	s_add_i32 s0, s0, 0x8000
	v_add_u32_e32 v217, s0, v215
	v_lshl_add_u32 v219, v210, 4, s0
	s_waitcnt lgkmcnt(0)
	s_barrier
	s_waitcnt vmcnt(15)
	ds_write_b64 v217, v[204:205]
	global_load_dwordx2 v[204:205], v[134:135], off offset:144
	s_cmp_lt_u32 s74, 4
	s_cbranch_scc1 .Lpf_do
	s_waitcnt vmcnt(0)
	s_branch .Lpf_done
.Lpf_do:
	s_cmp_lg_u64 s[50:51], 0
	s_mov_b32 s0, 0x2417
	s_cselect_b32 s0, 0x3560, s0
	s_lshl_b32 s1, s74, 2
	s_lshr_b32 s0, s0, s1
	s_and_b32 s36, s0, 15
	s_lshr_b32 s0, s87, 6
	s_lshl_b32 s1, s36, 8
	s_add_i32 s0, s0, s1
	v_or_b32_e32 v148, s0, v209
	v_add_u32_e32 v148, s46, v148
	v_lshlrev_b32_e32 v148, 11, v148
	v_add_co_u32_e32 v132, vcc, v182, v148
	s_lshl_b32 s0, s87, 2
	v_addc_co_u32_e32 v133, vcc, 0, v183, vcc
	s_add_i32 s0, s0, 0x18000
	s_mov_b32 m0, s0
	s_nop 0
	global_load_lds_dwordx4 v[132:133], off
	s_add_i32 m0, s0, 992
	s_nop 0
	global_load_lds_dwordx4 v[132:133], off offset:32
	s_add_i32 m0, s0, 1984
	s_nop 0
	global_load_lds_dwordx4 v[132:133], off offset:64
	s_add_i32 m0, s0, 2976
	s_nop 0
	global_load_lds_dwordx4 v[132:133], off offset:96
	s_add_i32 m0, s0, 3968
	s_nop 0
	global_load_lds_dwordx4 v[132:133], off offset:128
	s_add_i32 m0, s0, 4960
	s_nop 0
	global_load_lds_dwordx4 v[132:133], off offset:160
	s_add_i32 m0, s0, 5952
	s_nop 0
	global_load_lds_dwordx4 v[132:133], off offset:192
	s_add_i32 m0, s0, 6944
	s_nop 0
	global_load_lds_dwordx4 v[132:133], off offset:224
	s_lshl_b32 s0, s36, 2
	s_or_b32 s0, s0, 3
	s_lshl_b32 s0, s0, 17
	s_add_u32 s40, s76, s0
	s_addc_u32 s41, s77, 0
	s_add_u32 s66, s81, s0
	s_addc_u32 s67, s82, 0
	s_lshl_b32 s0, s36, 19
	s_or_b32 s36, s0, 0x40000
	s_add_u32 s0, s76, s36
	s_addc_u32 s1, s77, 0
	s_add_u32 s36, s81, s36
	s_addc_u32 s37, s82, 0
	s_mov_b32 m0, s88
	s_nop 0
	global_load_lds_dwordx4 v176, s[40:41] nt
	s_mov_b32 m0, s89
	s_nop 0
	global_load_lds_dwordx4 v190, s[66:67] nt
	s_mov_b32 m0, s91
	s_nop 0
	global_load_lds_dwordx4 v192, s[40:41] nt
	s_mov_b32 m0, s92
	s_nop 0
	global_load_lds_dwordx4 v194, s[66:67] nt
	s_mov_b32 m0, s93
	s_nop 0
	global_load_lds_dwordx4 v176, s[0:1] nt
	s_mov_b32 m0, s94
	s_nop 0
	global_load_lds_dwordx4 v190, s[36:37] nt
	s_mov_b32 m0, s95
	s_nop 0
	global_load_lds_dwordx4 v192, s[0:1] nt
	s_mov_b32 m0, s96
	s_nop 0
	global_load_lds_dwordx4 v194, s[36:37] nt
.Lpf_done:
	v_mov_b32_e32 v128, v197
	v_mov_b32_e32 v129, v196
	s_nop 0
	v_permlane32_swap_b32_e32 v197, v128
	v_permlane32_swap_b32_e32 v196, v129
	v_add_f32_e32 v148, v197, v128
	v_add_f32_e32 v149, v196, v129
	v_div_scale_f32 v150, s[0:1], v148, v148, 1.0
	v_div_scale_f32 v152, s[0:1], v149, v149, -v208
	v_rcp_f32_e32 v154, v150
	v_rcp_f32_e32 v155, v152
	v_div_scale_f32 v151, vcc, 1.0, v148, 1.0
	v_fma_f32 v156, -v150, v154, 1.0
	v_fma_f32 v157, -v152, v155, 1.0
	v_fmac_f32_e32 v154, v156, v154
	v_div_scale_f32 v153, s[36:37], -v208, v149, -v208
	v_fmac_f32_e32 v155, v157, v155
	v_mul_f32_e32 v156, v151, v154
	v_mul_f32_e32 v157, v153, v155
	v_fma_f32 v158, -v150, v156, v151
	v_fma_f32 v159, -v152, v157, v153
	v_fmac_f32_e32 v156, v158, v154
	v_fmac_f32_e32 v157, v159, v155
	v_fma_f32 v150, -v150, v156, v151
	v_fma_f32 v151, -v152, v157, v153
	v_div_fmas_f32 v150, v150, v154, v156
	s_mov_b64 vcc, s[36:37]
	v_div_fixup_f32 v148, v150, v148, 1.0
	v_div_fmas_f32 v150, v151, v155, v157
	v_div_fixup_f32 v150, v150, v149, -v208
	v_pk_mul_f32 v[96:97], v[96:97], v[150:151] op_sel_hi:[1,0]
	v_pk_mul_f32 v[98:99], v[98:99], v[150:151] op_sel_hi:[1,0]
	v_pk_fma_f32 v[112:113], v[112:113], v[148:149], v[96:97] op_sel_hi:[1,0,1]
	v_pk_fma_f32 v[114:115], v[114:115], v[148:149], v[98:99] op_sel_hi:[1,0,1]
	v_mul_f32_e32 v96, v113, v113
	v_pk_fma_f32 v[96:97], v[112:113], v[112:113], v[96:97] op_sel_hi:[1,1,0]
	v_pk_mul_f32 v[100:101], v[100:101], v[150:151] op_sel_hi:[1,0]
	v_mul_f32_e32 v98, v115, v115
	v_pk_fma_f32 v[96:97], v[114:115], v[114:115], v[96:97]
	v_pk_fma_f32 v[100:101], v[116:117], v[148:149], v[100:101] op_sel_hi:[1,0,1]
	v_pk_add_f32 v[96:97], v[98:99], v[96:97] op_sel_hi:[0,1]
	v_pk_mul_f32 v[102:103], v[102:103], v[150:151] op_sel_hi:[1,0]
	v_mul_f32_e32 v116, v101, v101
	v_pk_fma_f32 v[96:97], v[100:101], v[100:101], v[96:97]
	v_pk_fma_f32 v[102:103], v[118:119], v[148:149], v[102:103] op_sel_hi:[1,0,1]
	v_pk_add_f32 v[96:97], v[116:117], v[96:97] op_sel_hi:[0,1]
	v_pk_mul_f32 v[104:105], v[104:105], v[150:151] op_sel_hi:[1,0]
	v_mul_f32_e32 v118, v103, v103
	v_pk_fma_f32 v[96:97], v[102:103], v[102:103], v[96:97]
	v_pk_fma_f32 v[104:105], v[120:121], v[148:149], v[104:105] op_sel_hi:[1,0,1]
	v_pk_add_f32 v[96:97], v[118:119], v[96:97] op_sel_hi:[0,1]
	v_pk_mul_f32 v[106:107], v[106:107], v[150:151] op_sel_hi:[1,0]
	v_mul_f32_e32 v120, v105, v105
	v_pk_fma_f32 v[96:97], v[104:105], v[104:105], v[96:97]
	v_pk_fma_f32 v[106:107], v[122:123], v[148:149], v[106:107] op_sel_hi:[1,0,1]
	v_pk_add_f32 v[96:97], v[120:121], v[96:97] op_sel_hi:[0,1]
	v_pk_mul_f32 v[108:109], v[108:109], v[150:151] op_sel_hi:[1,0]
	v_mul_f32_e32 v122, v107, v107
	v_pk_fma_f32 v[96:97], v[106:107], v[106:107], v[96:97]
	v_pk_fma_f32 v[108:109], v[124:125], v[148:149], v[108:109] op_sel_hi:[1,0,1]
	v_pk_add_f32 v[96:97], v[122:123], v[96:97] op_sel_hi:[0,1]
	v_pk_mul_f32 v[110:111], v[110:111], v[150:151] op_sel_hi:[1,0]
	v_pk_fma_f32 v[96:97], v[108:109], v[108:109], v[96:97]
	v_mul_f32_e32 v98, v109, v109
	v_pk_fma_f32 v[110:111], v[126:127], v[148:149], v[110:111] op_sel_hi:[1,0,1]
	v_pk_add_f32 v[96:97], v[98:99], v[96:97] op_sel_hi:[0,1]
	v_pk_fma_f32 v[96:97], v[110:111], v[110:111], v[96:97]
	v_mul_f32_e32 v98, v111, v111
	v_pk_mul_f32 v[82:83], v[82:83], v[150:151] op_sel_hi:[1,0]
	v_pk_add_f32 v[118:119], v[98:99], v[96:97] op_sel_hi:[0,1]
	v_pk_fma_f32 v[96:97], v[66:67], v[148:149], v[82:83] op_sel_hi:[1,0,1]
	v_pk_mul_f32 v[66:67], v[80:81], v[150:151] op_sel_hi:[1,0]
	v_lshl_add_u64 v[132:133], v[130:131], 2, s[52:53]
	v_pk_fma_f32 v[98:99], v[64:65], v[148:149], v[66:67] op_sel_hi:[1,0,1]
	v_pk_fma_f32 v[64:65], v[98:99], v[98:99], v[118:119]
	v_mul_f32_e32 v66, v99, v99
	ds_read_b128 v[128:131], v219
	v_pk_add_f32 v[64:65], v[66:67], v[64:65] op_sel_hi:[0,1]
	v_pk_fma_f32 v[64:65], v[96:97], v[96:97], v[64:65]
	v_mul_f32_e32 v66, v97, v97
	v_pk_add_f32 v[64:65], v[66:67], v[64:65] op_sel_hi:[0,1]
	v_pk_mul_f32 v[66:67], v[86:87], v[150:151] op_sel_hi:[1,0]
	v_pk_mul_f32 v[50:51], v[50:51], v[150:151] op_sel_hi:[1,0]
	v_pk_fma_f32 v[80:81], v[70:71], v[148:149], v[66:67] op_sel_hi:[1,0,1]
	v_pk_mul_f32 v[66:67], v[84:85], v[150:151] op_sel_hi:[1,0]
	v_pk_mul_f32 v[18:19], v[18:19], v[150:151] op_sel_hi:[1,0]
	v_pk_fma_f32 v[82:83], v[68:69], v[148:149], v[66:67] op_sel_hi:[1,0,1]
	s_mov_b32 s0, 0x800000
	v_pk_fma_f32 v[64:65], v[82:83], v[82:83], v[64:65]
	v_mul_f32_e32 v66, v83, v83
	v_pk_add_f32 v[64:65], v[66:67], v[64:65] op_sel_hi:[0,1]
	v_pk_fma_f32 v[64:65], v[80:81], v[80:81], v[64:65]
	v_mul_f32_e32 v66, v81, v81
	v_pk_add_f32 v[64:65], v[66:67], v[64:65] op_sel_hi:[0,1]
	v_pk_mul_f32 v[66:67], v[90:91], v[150:151] op_sel_hi:[1,0]
	v_lshl_add_u64 v[140:141], s[68:69], 0, v[140:141]
	v_pk_fma_f32 v[74:75], v[74:75], v[148:149], v[66:67] op_sel_hi:[1,0,1]
	v_pk_mul_f32 v[66:67], v[88:89], v[150:151] op_sel_hi:[1,0]
	v_pk_fma_f32 v[72:73], v[72:73], v[148:149], v[66:67] op_sel_hi:[1,0,1]
	s_cmp_eq_u32 s74, 4
	v_pk_fma_f32 v[64:65], v[72:73], v[72:73], v[64:65]
	v_mul_f32_e32 v66, v73, v73
	v_pk_add_f32 v[64:65], v[66:67], v[64:65] op_sel_hi:[0,1]
	v_pk_fma_f32 v[64:65], v[74:75], v[74:75], v[64:65]
	v_mul_f32_e32 v66, v75, v75
	v_pk_add_f32 v[64:65], v[66:67], v[64:65] op_sel_hi:[0,1]
	v_pk_mul_f32 v[66:67], v[94:95], v[150:151] op_sel_hi:[1,0]
	s_waitcnt vmcnt(16) lgkmcnt(0)
	v_lshlrev_b32_e32 v116, 16, v160
	v_pk_fma_f32 v[68:69], v[78:79], v[148:149], v[66:67] op_sel_hi:[1,0,1]
	v_pk_mul_f32 v[66:67], v[92:93], v[150:151] op_sel_hi:[1,0]
	v_and_b32_e32 v117, 0xffff0000, v160
	v_pk_fma_f32 v[70:71], v[76:77], v[148:149], v[66:67] op_sel_hi:[1,0,1]
	s_nop 0
	v_pk_fma_f32 v[64:65], v[70:71], v[70:71], v[64:65]
	v_mul_f32_e32 v66, v71, v71
	v_pk_add_f32 v[64:65], v[66:67], v[64:65] op_sel_hi:[0,1]
	v_pk_fma_f32 v[64:65], v[68:69], v[68:69], v[64:65]
	v_mul_f32_e32 v66, v69, v69
	v_pk_add_f32 v[76:77], v[66:67], v[64:65] op_sel_hi:[0,1]
	v_pk_fma_f32 v[64:65], v[34:35], v[148:149], v[50:51] op_sel_hi:[1,0,1]
	v_pk_mul_f32 v[34:35], v[48:49], v[150:151] op_sel_hi:[1,0]
	s_nop 0
	v_pk_fma_f32 v[66:67], v[32:33], v[148:149], v[34:35] op_sel_hi:[1,0,1]
	s_nop 0
	v_pk_fma_f32 v[32:33], v[66:67], v[66:67], v[76:77]
	v_mul_f32_e32 v34, v67, v67
	v_pk_add_f32 v[32:33], v[34:35], v[32:33] op_sel_hi:[0,1]
	v_pk_fma_f32 v[32:33], v[64:65], v[64:65], v[32:33]
	v_mul_f32_e32 v34, v65, v65
	v_pk_add_f32 v[32:33], v[34:35], v[32:33] op_sel_hi:[0,1]
	v_pk_mul_f32 v[34:35], v[54:55], v[150:151] op_sel_hi:[1,0]
	s_nop 0
	v_pk_fma_f32 v[48:49], v[38:39], v[148:149], v[34:35] op_sel_hi:[1,0,1]
	v_pk_mul_f32 v[34:35], v[52:53], v[150:151] op_sel_hi:[1,0]
	s_nop 0
	v_pk_fma_f32 v[50:51], v[36:37], v[148:149], v[34:35] op_sel_hi:[1,0,1]
	s_nop 0
	v_pk_fma_f32 v[32:33], v[50:51], v[50:51], v[32:33]
	v_mul_f32_e32 v34, v51, v51
	v_pk_add_f32 v[32:33], v[34:35], v[32:33] op_sel_hi:[0,1]
	v_pk_fma_f32 v[32:33], v[48:49], v[48:49], v[32:33]
	v_mul_f32_e32 v34, v49, v49
	v_pk_add_f32 v[32:33], v[34:35], v[32:33] op_sel_hi:[0,1]
	v_pk_mul_f32 v[34:35], v[58:59], v[150:151] op_sel_hi:[1,0]
	s_nop 0
	v_pk_fma_f32 v[42:43], v[42:43], v[148:149], v[34:35] op_sel_hi:[1,0,1]
	v_pk_mul_f32 v[34:35], v[56:57], v[150:151] op_sel_hi:[1,0]
	s_nop 0
	v_pk_fma_f32 v[40:41], v[40:41], v[148:149], v[34:35] op_sel_hi:[1,0,1]
	s_nop 0
	v_pk_fma_f32 v[32:33], v[40:41], v[40:41], v[32:33]
	v_mul_f32_e32 v34, v41, v41
	v_pk_add_f32 v[32:33], v[34:35], v[32:33] op_sel_hi:[0,1]
	v_pk_fma_f32 v[32:33], v[42:43], v[42:43], v[32:33]
	v_mul_f32_e32 v34, v43, v43
	v_pk_add_f32 v[32:33], v[34:35], v[32:33] op_sel_hi:[0,1]
	v_pk_mul_f32 v[34:35], v[62:63], v[150:151] op_sel_hi:[1,0]
	s_nop 0
	v_pk_fma_f32 v[36:37], v[46:47], v[148:149], v[34:35] op_sel_hi:[1,0,1]
	v_pk_mul_f32 v[34:35], v[60:61], v[150:151] op_sel_hi:[1,0]
	s_nop 0
	v_pk_fma_f32 v[38:39], v[44:45], v[148:149], v[34:35] op_sel_hi:[1,0,1]
	s_nop 0
	v_pk_fma_f32 v[32:33], v[38:39], v[38:39], v[32:33]
	v_mul_f32_e32 v34, v39, v39
	v_pk_add_f32 v[32:33], v[34:35], v[32:33] op_sel_hi:[0,1]
	v_pk_fma_f32 v[32:33], v[36:37], v[36:37], v[32:33]
	v_mul_f32_e32 v34, v37, v37
	v_pk_add_f32 v[44:45], v[34:35], v[32:33] op_sel_hi:[0,1]
	v_pk_fma_f32 v[32:33], v[2:3], v[148:149], v[18:19] op_sel_hi:[1,0,1]
	v_pk_mul_f32 v[2:3], v[16:17], v[150:151] op_sel_hi:[1,0]
	s_nop 0
	v_pk_fma_f32 v[34:35], v[0:1], v[148:149], v[2:3] op_sel_hi:[1,0,1]
	s_nop 0
	v_pk_fma_f32 v[0:1], v[34:35], v[34:35], v[44:45]
	v_mul_f32_e32 v2, v35, v35
	v_pk_add_f32 v[0:1], v[2:3], v[0:1] op_sel_hi:[0,1]
	v_pk_fma_f32 v[0:1], v[32:33], v[32:33], v[0:1]
	v_mul_f32_e32 v2, v33, v33
	v_pk_add_f32 v[0:1], v[2:3], v[0:1] op_sel_hi:[0,1]
	v_pk_mul_f32 v[2:3], v[22:23], v[150:151] op_sel_hi:[1,0]
	v_lshlrev_b32_e32 v22, 16, v165
	v_pk_fma_f32 v[16:17], v[6:7], v[148:149], v[2:3] op_sel_hi:[1,0,1]
	v_pk_mul_f32 v[2:3], v[20:21], v[150:151] op_sel_hi:[1,0]
	v_and_b32_e32 v23, 0xffff0000, v165
	v_pk_fma_f32 v[18:19], v[4:5], v[148:149], v[2:3] op_sel_hi:[1,0,1]
	s_nop 0
	v_pk_fma_f32 v[0:1], v[18:19], v[18:19], v[0:1]
	v_mul_f32_e32 v2, v19, v19
	v_pk_add_f32 v[0:1], v[2:3], v[0:1] op_sel_hi:[0,1]
	v_pk_fma_f32 v[0:1], v[16:17], v[16:17], v[0:1]
	v_mul_f32_e32 v2, v17, v17
	v_pk_add_f32 v[0:1], v[2:3], v[0:1] op_sel_hi:[0,1]
	v_pk_mul_f32 v[2:3], v[26:27], v[150:151] op_sel_hi:[1,0]
	s_nop 0
	v_pk_fma_f32 v[10:11], v[10:11], v[148:149], v[2:3] op_sel_hi:[1,0,1]
	v_pk_mul_f32 v[2:3], v[24:25], v[150:151] op_sel_hi:[1,0]
	s_nop 0
	v_pk_fma_f32 v[8:9], v[8:9], v[148:149], v[2:3] op_sel_hi:[1,0,1]
	s_nop 0
	v_pk_fma_f32 v[0:1], v[8:9], v[8:9], v[0:1]
	v_mul_f32_e32 v2, v9, v9
	v_pk_add_f32 v[0:1], v[2:3], v[0:1] op_sel_hi:[0,1]
	v_pk_fma_f32 v[0:1], v[10:11], v[10:11], v[0:1]
	v_mul_f32_e32 v2, v11, v11
	v_pk_add_f32 v[4:5], v[2:3], v[0:1] op_sel_hi:[0,1]
	v_pk_mul_f32 v[2:3], v[28:29], v[150:151] op_sel_hi:[1,0]
	v_pk_mul_f32 v[0:1], v[30:31], v[150:151] op_sel_hi:[1,0]
	v_pk_fma_f32 v[2:3], v[12:13], v[148:149], v[2:3] op_sel_hi:[1,0,1]
	v_pk_fma_f32 v[0:1], v[14:15], v[148:149], v[0:1] op_sel_hi:[1,0,1]
	v_pk_fma_f32 v[4:5], v[2:3], v[2:3], v[4:5]
	v_mul_f32_e32 v6, v3, v3
	v_pk_add_f32 v[4:5], v[6:7], v[4:5] op_sel_hi:[0,1]
	v_pk_fma_f32 v[4:5], v[0:1], v[0:1], v[4:5]
	v_mul_f32_e32 v6, v1, v1
	v_pk_add_f32 v[4:5], v[6:7], v[4:5] op_sel_hi:[0,1]
	v_mov_b32_e32 v5, v4
	s_nop 1
	v_permlane32_swap_b32_e32 v4, v5
	v_add_f32_e32 v4, v4, v5
	v_fmamk_f32 v4, v4, 0x3c000000, v232
	v_mul_f32_e32 v5, 0x4b800000, v4
	v_cmp_gt_f32_e32 vcc, s0, v4
	v_lshlrev_b32_e32 v12, 16, v161
	v_and_b32_e32 v13, 0xffff0000, v161
	v_cndmask_b32_e32 v4, v4, v5, vcc
	v_rsq_f32_e32 v6, v4
	v_lshl_add_u64 v[4:5], v[140:141], 0, v[136:137]
	v_mul_f32_e32 v7, 0x45800000, v6
	v_cndmask_b32_e32 v6, v6, v7, vcc
	v_mul_f32_e32 v6, 0x3f077f5a, v6
	v_pk_mul_f32 v[14:15], v[112:113], v[6:7] op_sel_hi:[1,0]
	v_pk_mul_f32 v[20:21], v[114:115], v[6:7] op_sel_hi:[1,0]
	v_pk_mul_f32 v[14:15], v[128:129], v[14:15]
	v_pk_mul_f32 v[20:21], v[130:131], v[20:21]
	v_pk_mul_f32 v[14:15], v[14:15], v[116:117]
	v_pk_mul_f32 v[12:13], v[20:21], v[12:13]
	v_cvt_pk_bf16_f32 v14, v14, v15
	v_cvt_pk_bf16_f32 v15, v12, v13
	global_store_dwordx2 v[4:5], v[14:15], off
	ds_read_b128 v[12:15], v219 offset:32
	v_pk_mul_f32 v[20:21], v[100:101], v[6:7] op_sel_hi:[1,0]
	v_pk_mul_f32 v[24:25], v[104:105], v[6:7] op_sel_hi:[1,0]
	v_pk_mul_f32 v[26:27], v[106:107], v[6:7] op_sel_hi:[1,0]
	v_pk_mul_f32 v[28:29], v[110:111], v[6:7] op_sel_hi:[1,0]
	v_pk_mul_f32 v[30:31], v[98:99], v[6:7] op_sel_hi:[1,0]
	v_pk_mul_f32 v[44:45], v[96:97], v[6:7] op_sel_hi:[1,0]
	v_pk_mul_f32 v[32:33], v[32:33], v[6:7] op_sel_hi:[1,0]
	v_pk_mul_f32 v[18:19], v[18:19], v[6:7] op_sel_hi:[1,0]
	v_pk_mul_f32 v[16:17], v[16:17], v[6:7] op_sel_hi:[1,0]
	v_pk_mul_f32 v[8:9], v[8:9], v[6:7] op_sel_hi:[1,0]
	v_pk_mul_f32 v[10:11], v[10:11], v[6:7] op_sel_hi:[1,0]
	v_pk_mul_f32 v[2:3], v[2:3], v[6:7] op_sel_hi:[1,0]
	v_pk_mul_f32 v[0:1], v[0:1], v[6:7] op_sel_hi:[1,0]
	s_waitcnt lgkmcnt(0)
	v_pk_mul_f32 v[12:13], v[12:13], v[20:21]
	v_lshlrev_b32_e32 v20, 16, v162
	v_and_b32_e32 v21, 0xffff0000, v162
	v_pk_mul_f32 v[12:13], v[12:13], v[20:21]
	v_pk_mul_f32 v[20:21], v[102:103], v[6:7] op_sel_hi:[1,0]
	v_cvt_pk_bf16_f32 v12, v12, v13
	v_pk_mul_f32 v[14:15], v[14:15], v[20:21]
	v_lshlrev_b32_e32 v20, 16, v163
	v_and_b32_e32 v21, 0xffff0000, v163
	v_pk_mul_f32 v[14:15], v[14:15], v[20:21]
	v_lshlrev_b32_e32 v20, 16, v164
	v_cvt_pk_bf16_f32 v13, v14, v15
	global_store_dwordx2 v[4:5], v[12:13], off offset:16
	ds_read_b128 v[12:15], v219 offset:64
	v_and_b32_e32 v21, 0xffff0000, v164
	s_waitcnt lgkmcnt(0)
	v_pk_mul_f32 v[12:13], v[12:13], v[24:25]
	v_pk_mul_f32 v[14:15], v[14:15], v[26:27]
	v_pk_mul_f32 v[12:13], v[12:13], v[20:21]
	v_pk_mul_f32 v[14:15], v[14:15], v[22:23]
	v_cvt_pk_bf16_f32 v12, v12, v13
	v_cvt_pk_bf16_f32 v13, v14, v15
	global_store_dwordx2 v[4:5], v[12:13], off offset:32
	ds_read_b128 v[12:15], v219 offset:96
	s_nop 0
	v_pk_mul_f32 v[26:27], v[108:109], v[6:7] op_sel_hi:[1,0]
	v_lshlrev_b32_e32 v22, 16, v166
	v_and_b32_e32 v23, 0xffff0000, v166
	v_lshlrev_b32_e32 v24, 16, v167
	v_and_b32_e32 v25, 0xffff0000, v167
	s_waitcnt lgkmcnt(0)
	v_pk_mul_f32 v[12:13], v[12:13], v[26:27]
	v_pk_mul_f32 v[14:15], v[14:15], v[28:29]
	v_pk_mul_f32 v[12:13], v[12:13], v[22:23]
	v_pk_mul_f32 v[14:15], v[14:15], v[24:25]
	v_cvt_pk_bf16_f32 v12, v12, v13
	v_cvt_pk_bf16_f32 v13, v14, v15
	global_store_dwordx2 v[4:5], v[12:13], off offset:48
	ds_read_b128 v[12:15], v219 offset:128
	s_nop 0
	v_lshlrev_b32_e32 v28, 16, v168
	v_and_b32_e32 v29, 0xffff0000, v168
	v_lshlrev_b32_e32 v20, 16, v169
	v_and_b32_e32 v21, 0xffff0000, v169
	s_waitcnt lgkmcnt(0)
	v_pk_mul_f32 v[12:13], v[30:31], v[12:13]
	v_pk_mul_f32 v[14:15], v[44:45], v[14:15]
	v_pk_mul_f32 v[12:13], v[12:13], v[28:29]
	v_pk_mul_f32 v[14:15], v[14:15], v[20:21]
	v_cvt_pk_bf16_f32 v12, v12, v13
	v_cvt_pk_bf16_f32 v13, v14, v15
	global_store_dwordx2 v[4:5], v[12:13], off offset:64
	ds_read_b128 v[12:15], v219 offset:160
	v_pk_mul_f32 v[28:29], v[82:83], v[6:7] op_sel_hi:[1,0]
	v_pk_mul_f32 v[30:31], v[80:81], v[6:7] op_sel_hi:[1,0]
	v_lshlrev_b32_e32 v20, 16, v170
	v_and_b32_e32 v21, 0xffff0000, v170
	v_lshlrev_b32_e32 v22, 16, v171
	v_and_b32_e32 v23, 0xffff0000, v171
	v_pk_mul_f32 v[44:45], v[64:65], v[6:7] op_sel_hi:[1,0]
	s_waitcnt lgkmcnt(0)
	v_pk_mul_f32 v[12:13], v[28:29], v[12:13]
	v_pk_mul_f32 v[14:15], v[30:31], v[14:15]
	v_pk_mul_f32 v[12:13], v[12:13], v[20:21]
	v_pk_mul_f32 v[14:15], v[14:15], v[22:23]
	v_cvt_pk_bf16_f32 v12, v12, v13
	v_cvt_pk_bf16_f32 v13, v14, v15
	global_store_dwordx2 v[4:5], v[12:13], off offset:80
	ds_read_b128 v[12:15], v219 offset:192
	v_lshlrev_b32_e32 v20, 16, v172
	v_and_b32_e32 v21, 0xffff0000, v172
	v_lshlrev_b32_e32 v22, 16, v173
	v_and_b32_e32 v23, 0xffff0000, v173
	v_pk_mul_f32 v[24:25], v[72:73], v[6:7] op_sel_hi:[1,0]
	v_pk_mul_f32 v[28:29], v[74:75], v[6:7] op_sel_hi:[1,0]
	v_pk_mul_f32 v[30:31], v[66:67], v[6:7] op_sel_hi:[1,0]
	s_waitcnt lgkmcnt(0)
	v_pk_mul_f32 v[12:13], v[24:25], v[12:13]
	v_pk_mul_f32 v[14:15], v[28:29], v[14:15]
	v_pk_mul_f32 v[12:13], v[12:13], v[20:21]
	v_pk_mul_f32 v[14:15], v[14:15], v[22:23]
	v_cvt_pk_bf16_f32 v12, v12, v13
	v_cvt_pk_bf16_f32 v13, v14, v15
	global_store_dwordx2 v[4:5], v[12:13], off offset:96
	ds_read_b128 v[12:15], v219 offset:224
	s_nop 0
	v_lshlrev_b32_e32 v22, 16, v174
	v_and_b32_e32 v23, 0xffff0000, v174
	v_lshlrev_b32_e32 v24, 16, v175
	v_and_b32_e32 v25, 0xffff0000, v175
	v_pk_mul_f32 v[26:27], v[70:71], v[6:7] op_sel_hi:[1,0]
	v_pk_mul_f32 v[28:29], v[68:69], v[6:7] op_sel_hi:[1,0]
	s_waitcnt lgkmcnt(0)
	v_pk_mul_f32 v[12:13], v[26:27], v[12:13]
	v_pk_mul_f32 v[14:15], v[28:29], v[14:15]
	v_pk_mul_f32 v[12:13], v[12:13], v[22:23]
	v_pk_mul_f32 v[14:15], v[14:15], v[24:25]
	v_cvt_pk_bf16_f32 v12, v12, v13
	v_cvt_pk_bf16_f32 v13, v14, v15
	global_store_dwordx2 v[4:5], v[12:13], off offset:112
	ds_read_b128 v[12:15], v219 offset:256
	s_nop 0
	v_lshlrev_b32_e32 v28, 16, v202
	v_and_b32_e32 v29, 0xffff0000, v202
	v_lshlrev_b32_e32 v20, 16, v203
	v_and_b32_e32 v21, 0xffff0000, v203
	s_waitcnt lgkmcnt(0)
	v_pk_mul_f32 v[12:13], v[30:31], v[12:13]
	v_pk_mul_f32 v[14:15], v[44:45], v[14:15]
	v_pk_mul_f32 v[12:13], v[12:13], v[28:29]
	v_pk_mul_f32 v[14:15], v[14:15], v[20:21]
	v_cvt_pk_bf16_f32 v12, v12, v13
	v_cvt_pk_bf16_f32 v13, v14, v15
	global_store_dwordx2 v[4:5], v[12:13], off offset:128
	ds_read_b128 v[12:15], v219 offset:288
	v_pk_mul_f32 v[28:29], v[50:51], v[6:7] op_sel_hi:[1,0]
	v_pk_mul_f32 v[30:31], v[48:49], v[6:7] op_sel_hi:[1,0]
	v_lshlrev_b32_e32 v20, 16, v204
	v_and_b32_e32 v21, 0xffff0000, v204
	v_lshlrev_b32_e32 v22, 16, v205
	v_and_b32_e32 v23, 0xffff0000, v205
	s_waitcnt lgkmcnt(0)
	v_pk_mul_f32 v[12:13], v[28:29], v[12:13]
	v_pk_mul_f32 v[14:15], v[30:31], v[14:15]
	v_pk_mul_f32 v[12:13], v[12:13], v[20:21]
	v_pk_mul_f32 v[14:15], v[14:15], v[22:23]
	v_cvt_pk_bf16_f32 v12, v12, v13
	v_cvt_pk_bf16_f32 v13, v14, v15
	global_store_dwordx2 v[4:5], v[12:13], off offset:144
	ds_read_b128 v[12:15], v219 offset:320
	v_lshlrev_b32_e32 v20, 16, v244
	v_and_b32_e32 v21, 0xffff0000, v244
	v_lshlrev_b32_e32 v22, 16, v245
	v_and_b32_e32 v23, 0xffff0000, v245
	v_pk_mul_f32 v[24:25], v[40:41], v[6:7] op_sel_hi:[1,0]
	v_pk_mul_f32 v[28:29], v[42:43], v[6:7] op_sel_hi:[1,0]
	v_pk_mul_f32 v[30:31], v[34:35], v[6:7] op_sel_hi:[1,0]
	s_waitcnt lgkmcnt(0)
	v_pk_mul_f32 v[12:13], v[24:25], v[12:13]
	v_pk_mul_f32 v[14:15], v[28:29], v[14:15]
	v_pk_mul_f32 v[12:13], v[12:13], v[20:21]
	v_pk_mul_f32 v[14:15], v[14:15], v[22:23]
	v_cvt_pk_bf16_f32 v12, v12, v13
	v_cvt_pk_bf16_f32 v13, v14, v15
	global_store_dwordx2 v[4:5], v[12:13], off offset:160
	ds_read_b128 v[12:15], v219 offset:352
	s_nop 0
	v_lshlrev_b32_e32 v22, 16, v246
	v_and_b32_e32 v23, 0xffff0000, v246
	v_lshlrev_b32_e32 v24, 16, v247
	v_and_b32_e32 v25, 0xffff0000, v247
	v_pk_mul_f32 v[26:27], v[38:39], v[6:7] op_sel_hi:[1,0]
	v_pk_mul_f32 v[28:29], v[36:37], v[6:7] op_sel_hi:[1,0]
	s_waitcnt lgkmcnt(0)
	v_pk_mul_f32 v[12:13], v[26:27], v[12:13]
	v_pk_mul_f32 v[14:15], v[28:29], v[14:15]
	v_pk_mul_f32 v[12:13], v[12:13], v[22:23]
	v_pk_mul_f32 v[14:15], v[14:15], v[24:25]
	v_cvt_pk_bf16_f32 v12, v12, v13
	v_cvt_pk_bf16_f32 v13, v14, v15
	global_store_dwordx2 v[4:5], v[12:13], off offset:176
	ds_read_b128 v[12:15], v219 offset:384
	s_nop 0
	v_lshlrev_b32_e32 v28, 16, v248
	v_and_b32_e32 v29, 0xffff0000, v248
	v_lshlrev_b32_e32 v20, 16, v249
	v_and_b32_e32 v21, 0xffff0000, v249
	s_waitcnt lgkmcnt(0)
	v_pk_mul_f32 v[12:13], v[30:31], v[12:13]
	v_pk_mul_f32 v[14:15], v[32:33], v[14:15]
	v_pk_mul_f32 v[12:13], v[12:13], v[28:29]
	v_pk_mul_f32 v[14:15], v[14:15], v[20:21]
	v_cvt_pk_bf16_f32 v12, v12, v13
	v_cvt_pk_bf16_f32 v13, v14, v15
	global_store_dwordx2 v[4:5], v[12:13], off offset:192
	ds_read_b128 v[12:15], v219 offset:416
	v_lshlrev_b32_e32 v20, 16, v250
	v_and_b32_e32 v21, 0xffff0000, v250
	v_lshlrev_b32_e32 v22, 16, v251
	v_and_b32_e32 v23, 0xffff0000, v251
	s_waitcnt lgkmcnt(0)
	v_pk_mul_f32 v[12:13], v[18:19], v[12:13]
	v_pk_mul_f32 v[14:15], v[16:17], v[14:15]
	v_pk_mul_f32 v[12:13], v[12:13], v[20:21]
	v_pk_mul_f32 v[14:15], v[14:15], v[22:23]
	v_cvt_pk_bf16_f32 v12, v12, v13
	v_cvt_pk_bf16_f32 v13, v14, v15
	global_store_dwordx2 v[4:5], v[12:13], off offset:208
	ds_read_b128 v[12:15], v219 offset:448
	v_lshlrev_b32_e32 v16, 16, v252
	v_and_b32_e32 v17, 0xffff0000, v252
	v_lshlrev_b32_e32 v18, 16, v253
	v_and_b32_e32 v19, 0xffff0000, v253
	s_waitcnt lgkmcnt(0)
	v_pk_mul_f32 v[8:9], v[8:9], v[12:13]
	v_pk_mul_f32 v[10:11], v[10:11], v[14:15]
	v_pk_mul_f32 v[8:9], v[8:9], v[16:17]
	v_pk_mul_f32 v[10:11], v[10:11], v[18:19]
	v_cvt_pk_bf16_f32 v8, v8, v9
	v_cvt_pk_bf16_f32 v9, v10, v11
	global_store_dwordx2 v[4:5], v[8:9], off offset:224
	ds_read_b128 v[8:11], v219 offset:480
	v_lshlrev_b32_e32 v12, 16, v254
	v_and_b32_e32 v13, 0xffff0000, v254
	v_lshlrev_b32_e32 v14, 16, v255
	v_and_b32_e32 v15, 0xffff0000, v255
	s_waitcnt lgkmcnt(0)
	v_pk_mul_f32 v[2:3], v[2:3], v[8:9]
	v_pk_mul_f32 v[0:1], v[0:1], v[10:11]
	v_pk_mul_f32 v[2:3], v[2:3], v[12:13]
	v_pk_mul_f32 v[0:1], v[0:1], v[14:15]
	v_cvt_pk_bf16_f32 v2, v2, v3
	v_cvt_pk_bf16_f32 v3, v0, v1
	global_store_dwordx2 v[4:5], v[2:3], off offset:240
	s_cbranch_scc1 .LBB0_735

.LBB0_751:
	v_readfirstlane_b32 s1, v207
	s_lshr_b32 s0, s1, 6
	s_lshl_b32 s37, s36, 8
	s_lshl_b32 s79, s0, 5
	s_add_i32 s37, s79, s37
	v_or_b32_e32 v188, s37, v209
	v_add_u32_e32 v176, s46, v188
	v_lshlrev_b64 v[0:1], 11, v[176:177]
	v_lshl_add_u64 v[4:5], v[182:183], 0, v[0:1]
	s_cmp_lg_u32 s74, 0
	s_cbranch_scc1 .Lpf_q1
	global_load_dwordx4 v[144:147], v[4:5], off
	global_load_dwordx4 v[148:151], v[4:5], off offset:32
	global_load_dwordx4 v[152:155], v[4:5], off offset:64
	global_load_dwordx4 v[156:159], v[4:5], off offset:96
	global_load_dwordx4 v[160:163], v[4:5], off offset:128
	global_load_dwordx4 v[164:167], v[4:5], off offset:160
	global_load_dwordx4 v[168:171], v[4:5], off offset:192
	global_load_dwordx4 v[172:175], v[4:5], off offset:224
.Lpf_q1:
	s_lshl_b32 s37, s0, 13
	v_add_u32_e32 v189, s37, v211
	s_lshl_b32 s37, s0, 3
	v_or_b32_e32 v16, s37, v212
	v_bitop3_b32 v17, s37, v207, v212 bitop3:0x36
	s_lshr_b32 s1, s1, 5
	v_lshlrev_b32_e32 v16, 11, v16
	v_lshlrev_b32_e32 v17, 4, v17
	s_and_b32 s1, s1, 2
	v_and_or_b32 v176, v17, s70, v16
	v_bitop3_b32 v17, s1, v213, v214 bitop3:0x36
	s_or_b32 s1, s37, 4
	s_lshl_b32 s83, s36, 2
	v_lshl_or_b32 v190, v17, 4, v16
	v_or_b32_e32 v16, s1, v212
	v_bitop3_b32 v17, s1, v207, v212 bitop3:0x36
	s_lshl_b32 s38, s36, 3
	v_lshlrev_b32_e32 v16, 11, v16
	v_lshlrev_b32_e32 v17, 4, v17
	s_bfe_u32 s1, s1, 0x20002
	s_or_b32 s86, s83, 3
	v_and_or_b32 v192, v17, s70, v16
	v_bitop3_b32 v17, s1, v213, v214 bitop3:0x36
	s_add_i32 s84, s0, s38
	s_add_i32 s85, s83, 4
	s_lshl_b32 s1, s86, 17
	s_add_u32 s40, s76, s1
	s_addc_u32 s41, s77, 0
	s_add_u32 s66, s81, s1
	s_addc_u32 s67, s82, 0
	s_lshl_b32 s87, s0, 11
	s_add_i32 s88, s87, 0
	s_lshl_b32 s0, s36, 19
	s_add_i32 s89, s88, 0xc000
	s_or_b32 s90, s87, 0x400
	s_add_i32 s91, s88, 0x400
	s_add_i32 s92, s88, 0xc400
	s_or_b32 s36, s0, 0x40000
	s_mov_b32 m0, s88
	s_add_u32 s0, s76, s36
	s_addc_u32 s1, s77, 0
	s_add_u32 s36, s81, s36
	v_lshl_or_b32 v194, v17, 4, v16
	s_addc_u32 s37, s82, 0
	s_add_i32 s93, s88, 0x4000
	s_add_i32 s94, s71, s87
	s_add_i32 s95, s88, 0x4400
	s_add_i32 s96, s71, s90
	v_mov_b32_e32 v185, v184
	v_mov_b32_e32 v96, v177
	v_mov_b32_e32 v97, v177
	v_mov_b32_e32 v110, v177
	v_mov_b32_e32 v111, v177
	v_mov_b32_e32 v98, v177
	v_mov_b32_e32 v99, v177
	v_mov_b32_e32 v100, v177
	v_mov_b32_e32 v101, v177
	v_mov_b32_e32 v102, v177
	v_mov_b32_e32 v103, v177
	v_mov_b32_e32 v104, v177
	v_mov_b32_e32 v105, v177
	v_mov_b32_e32 v106, v177
	v_mov_b32_e32 v107, v177
	v_mov_b32_e32 v108, v177
	v_mov_b32_e32 v109, v177
	v_mov_b64_e32 v[64:65], v[96:97]
	v_mov_b64_e32 v[80:81], v[96:97]
	v_mov_b64_e32 v[32:33], v[96:97]
	v_mov_b64_e32 v[48:49], v[96:97]
	v_mov_b64_e32 v[126:127], v[110:111]
	v_mov_b32_e32 v191, v177
	v_mov_b32_e32 v193, v177
	v_mov_b32_e32 v195, v177
	s_sub_i32 s97, s79, 64
	s_add_i32 s65, s79, 0xffffffa0
	s_or_b32 s38, s38, 6
	s_add_i32 s39, s79, 0xffffff80
	v_mov_b32_e32 v196, v177
	v_mov_b32_e32 v197, v177
	v_mov_b32_e32 v199, 0xf149f2ca
	v_mov_b32_e32 v201, 0xf149f2ca
	v_mov_b64_e32 v[66:67], v[98:99]
	v_mov_b64_e32 v[68:69], v[100:101]
	v_mov_b64_e32 v[70:71], v[102:103]
	v_mov_b64_e32 v[72:73], v[104:105]
	v_mov_b64_e32 v[74:75], v[106:107]
	v_mov_b64_e32 v[76:77], v[108:109]
	v_mov_b64_e32 v[78:79], v[110:111]
	v_mov_b64_e32 v[82:83], v[98:99]
	v_mov_b64_e32 v[84:85], v[100:101]
	v_mov_b64_e32 v[86:87], v[102:103]
	v_mov_b64_e32 v[88:89], v[104:105]
	v_mov_b64_e32 v[90:91], v[106:107]
	v_mov_b64_e32 v[92:93], v[108:109]
	v_mov_b64_e32 v[94:95], v[110:111]
	v_mov_b64_e32 v[34:35], v[98:99]
	v_mov_b64_e32 v[36:37], v[100:101]
	v_mov_b64_e32 v[38:39], v[102:103]
	v_mov_b64_e32 v[40:41], v[104:105]
	v_mov_b64_e32 v[42:43], v[106:107]
	v_mov_b64_e32 v[44:45], v[108:109]
	v_mov_b64_e32 v[46:47], v[110:111]
	v_mov_b64_e32 v[50:51], v[98:99]
	v_mov_b64_e32 v[52:53], v[100:101]
	v_mov_b64_e32 v[54:55], v[102:103]
	v_mov_b64_e32 v[56:57], v[104:105]
	v_mov_b64_e32 v[58:59], v[106:107]
	v_mov_b64_e32 v[60:61], v[108:109]
	v_mov_b64_e32 v[62:63], v[110:111]
	v_mov_b64_e32 v[124:125], v[108:109]
	v_mov_b64_e32 v[122:123], v[106:107]
	v_mov_b64_e32 v[120:121], v[104:105]
	v_mov_b64_e32 v[118:119], v[102:103]
	v_mov_b64_e32 v[116:117], v[100:101]
	v_mov_b64_e32 v[114:115], v[98:99]
	v_mov_b64_e32 v[112:113], v[96:97]
	v_mov_b32_e32 v0, v210
	s_cmp_lg_u32 s74, 0
	s_cbranch_scc1 .Lpf_q2
	s_mov_b32 m0, s88
	s_nop 0
	global_load_lds_dwordx4 v176, s[40:41] nt
	s_mov_b32 m0, s89
	s_nop 0
	global_load_lds_dwordx4 v190, s[66:67] nt
	s_mov_b32 m0, s91
	s_nop 0
	global_load_lds_dwordx4 v192, s[40:41] nt
	s_mov_b32 m0, s92
	s_nop 0
	global_load_lds_dwordx4 v194, s[66:67] nt
	s_mov_b32 m0, s93
	s_nop 0
	global_load_lds_dwordx4 v176, s[0:1] nt
	s_mov_b32 m0, s94
	s_nop 0
	global_load_lds_dwordx4 v190, s[36:37] nt
	s_mov_b32 m0, s95
	s_nop 0
	global_load_lds_dwordx4 v192, s[0:1] nt
	s_mov_b32 m0, s96
	s_nop 0
	global_load_lds_dwordx4 v194, s[36:37] nt
	s_waitcnt vmcnt(8)
	ds_write_b128 v189, v[144:147]
	ds_write_b128 v189, v[148:151] offset:1024
	ds_write_b128 v189, v[152:155] offset:2048
	ds_write_b128 v189, v[156:159] offset:3072
	ds_write_b128 v189, v[160:163] offset:4096
	ds_write_b128 v189, v[164:167] offset:5120
	ds_write_b128 v189, v[168:171] offset:6144
	ds_write_b128 v189, v[172:175] offset:7168
.Lpf_q2:
	v_lshlrev_b32_e32 v0, 3, v0
	v_add_u32_e32 v2, 16, v0
	v_or_b32_e32 v1, 1, v0
	v_or_b32_e32 v4, 3, v0
	v_or_b32_e32 v5, 2, v0
	v_or_b32_e32 v6, 5, v0
	v_or_b32_e32 v7, 4, v0
	v_or_b32_e32 v8, 7, v0
	v_or_b32_e32 v9, 6, v0
	v_add_u32_e32 v3, 17, v0
	v_or_b32_e32 v10, 3, v2
	v_or_b32_e32 v11, 2, v2
	v_or_b32_e32 v12, 5, v2
	v_or_b32_e32 v13, 4, v2
	v_or_b32_e32 v14, 7, v2
	v_or_b32_e32 v15, 6, v2
	v_cvt_f32_i32_e32 v17, v10
	v_cvt_f32_i32_e32 v16, v11
	v_cvt_f32_i32_e32 v11, v12
	v_cvt_f32_i32_e32 v10, v13
	v_cvt_f32_i32_e32 v13, v14
	v_cvt_f32_i32_e32 v12, v15
	v_cvt_f32_i32_e32 v15, v4
	v_cvt_f32_i32_e32 v14, v5
	v_cvt_f32_i32_e32 v5, v6
	v_cvt_f32_i32_e32 v4, v7
	v_cvt_f32_i32_e32 v7, v8
	v_cvt_f32_i32_e32 v6, v9
	v_cvt_f32_i32_e32 v0, v0
	v_cvt_f32_i32_e32 v1, v1
	v_cvt_f32_i32_e32 v3, v3
	v_cvt_f32_i32_e32 v2, v2
	v_pk_mul_f32 v[134:135], v[184:185], v[6:7]
	v_pk_mul_f32 v[132:133], v[184:185], v[4:5]
	v_pk_mul_f32 v[130:131], v[184:185], v[14:15]
	v_pk_mul_f32 v[142:143], v[184:185], v[12:13]
	v_pk_mul_f32 v[140:141], v[184:185], v[10:11]
	v_pk_mul_f32 v[138:139], v[184:185], v[16:17]
	v_pk_mul_f32 v[136:137], v[184:185], v[2:3]
	v_pk_mul_f32 v[128:129], v[186:187], v[0:1]
	v_mov_b64_e32 v[0:1], v[96:97]
	v_mov_b64_e32 v[16:17], v[96:97]
	s_or_b32 s36, s83, 2
	s_or_b32 s37, s83, 1
	v_subrev_u32_e32 v185, s79, v231
	s_add_i32 s66, s79, 0xffffff60
	s_add_i32 s67, s79, 0xffffff40
	s_addk_i32 s79, 0xff20
	s_mov_b32 s40, 0
	s_mov_b32 s41, 0
	v_mov_b64_e32 v[2:3], v[98:99]
	v_mov_b64_e32 v[4:5], v[100:101]
	v_mov_b64_e32 v[6:7], v[102:103]
	v_mov_b64_e32 v[8:9], v[104:105]
	v_mov_b64_e32 v[10:11], v[106:107]
	v_mov_b64_e32 v[12:13], v[108:109]
	v_mov_b64_e32 v[14:15], v[110:111]
	v_mov_b64_e32 v[18:19], v[98:99]
	v_mov_b64_e32 v[20:21], v[100:101]
	v_mov_b64_e32 v[22:23], v[102:103]
	v_mov_b64_e32 v[24:25], v[104:105]
	v_mov_b64_e32 v[26:27], v[106:107]
	v_mov_b64_e32 v[28:29], v[108:109]
	v_mov_b64_e32 v[30:31], v[110:111]
	s_branch .LBB0_754
